# attention unit boundary: exchange barrier no longer drains vmcnt (next unit K/V tiles keep landing during exchange/epilogue); epilogue waves issue next-unit Q loads at epilogue start
# baseline (speedup 1.0000x reference)
.LBB0_1151:
	s_andn2_b64 vcc, exec, s[4:5]
	s_waitcnt lgkmcnt(0)
	s_barrier
	s_cbranch_vccnz .LBB0_1153
	s_lshl_b32 s8, s35, 7
	s_and_b32 s8, s8, 0xf80
	s_add_i32 s8, s8, s18
	s_ashr_i32 s9, s8, 31
	v_lshl_add_u64 v[64:65], v[184:185], 0, s[8:9]
	v_lshlrev_b64 v[64:65], 11, v[64:65]
	v_lshl_add_u64 v[64:65], v[64:65], 0, s[52:53]
	v_lshlrev_b64 v[80:81], 1, v[64:65]
	v_lshl_add_u64 v[68:69], v[190:191], 0, v[80:81]
	global_load_dwordx2 v[98:99], v[68:69], off
	s_andn2_b64 vcc, exec, s[36:37]
	s_cbranch_vccnz .Lq_early_skip
	s_lshr_b32 s8, s12, 5
	s_or_b32 s13, s8, s21
	s_lshl_b32 s8, s12, 7
	s_and_b32 s8, s8, 0xf80
	s_add_i32 s8, s8, s18
	s_ashr_i32 s9, s8, 31
	v_lshl_add_u64 v[142:143], s[8:9], 0, v[186:187]
	v_lshlrev_b64 v[142:143], 12, v[142:143]
	v_lshl_add_u64 v[142:143], s[22:23], 0, v[142:143]
	s_lshl_b32 s52, s13, 8
	v_lshl_add_u64 v[142:143], v[142:143], 0, s[52:53]
	s_mov_b32 s35, s53
	v_lshl_add_u64 v[142:143], v[142:143], 0, s[34:35]
	v_mov_b32_e32 v201, v176
	v_lshl_add_u64 v[142:143], v[142:143], 0, v[200:201]
	global_load_dwordx4 v[128:131], v[142:143], off
	global_load_dwordx4 v[132:135], v[142:143], off offset:32
	global_load_dwordx4 v[136:139], v[142:143], off offset:64
	global_load_dwordx4 v[140:143], v[142:143], off offset:96
.Lq_early_skip:
	ds_read2st64_b32 v[70:71], v245 offset1:1
	ds_read2st64_b32 v[72:73], v245 offset0:2 offset1:3
	ds_read2st64_b32 v[76:77], v245 offset0:4 offset1:5
	ds_read2st64_b32 v[74:75], v245 offset0:6 offset1:7
	ds_read2st64_b32 v[126:127], v245 offset0:8 offset1:9
	ds_read2st64_b32 v[144:145], v245 offset0:10 offset1:11
	ds_read2st64_b32 v[146:147], v245 offset0:12 offset1:13
	ds_read2st64_b32 v[148:149], v245 offset0:14 offset1:15
	ds_read2st64_b32 v[150:151], v245 offset0:16 offset1:17
	ds_read2st64_b32 v[152:153], v245 offset0:18 offset1:19
	ds_read2st64_b32 v[124:125], v245 offset0:20 offset1:21
	ds_read2st64_b32 v[154:155], v245 offset0:22 offset1:23
	ds_read2st64_b32 v[120:121], v245 offset0:24 offset1:25
	ds_read2st64_b32 v[122:123], v245 offset0:26 offset1:27
	ds_read2st64_b32 v[116:117], v245 offset0:28 offset1:29
	ds_read2st64_b32 v[118:119], v245 offset0:30 offset1:31
	ds_read2st64_b32 v[110:111], v245 offset0:32 offset1:33
	ds_read2st64_b32 v[114:115], v245 offset0:34 offset1:35
	ds_read2st64_b32 v[104:105], v245 offset0:36 offset1:37
	ds_read2st64_b32 v[112:113], v245 offset0:38 offset1:39
	ds_read2st64_b32 v[96:97], v245 offset0:40 offset1:41
	ds_read2st64_b32 v[108:109], v245 offset0:42 offset1:43
	ds_read2st64_b32 v[92:93], v245 offset0:44 offset1:45
	ds_read2st64_b32 v[102:103], v245 offset0:46 offset1:47
	ds_read2st64_b32 v[86:87], v245 offset0:56 offset1:57
	ds_read2st64_b32 v[88:89], v245 offset0:58 offset1:59
	ds_read2st64_b32 v[82:83], v245 offset0:60 offset1:61
	ds_read2st64_b32 v[84:85], v245 offset0:62 offset1:63
	ds_read2st64_b32 v[94:95], v245 offset0:48 offset1:49
	ds_read2st64_b32 v[106:107], v245 offset0:50 offset1:51
	ds_read2st64_b32 v[90:91], v245 offset0:52 offset1:53
	ds_read2st64_b32 v[100:101], v245 offset0:54 offset1:55
	s_waitcnt lgkmcnt(4)
	v_pk_fma_f32 v[14:15], v[14:15], v[78:79], v[84:85] op_sel_hi:[1,0,1] neg_lo:[0,0,1] neg_hi:[0,0,1]
	v_pk_fma_f32 v[84:85], v[48:49], v[78:79], v[70:71] op_sel_hi:[1,0,1] neg_lo:[0,0,1] neg_hi:[0,0,1]
	v_pk_fma_f32 v[48:49], v[40:41], v[78:79], v[120:121] op_sel_hi:[1,0,1] neg_lo:[0,0,1] neg_hi:[0,0,1]
	v_pk_fma_f32 v[40:41], v[46:47], v[78:79], v[118:119] op_sel_hi:[1,0,1] neg_lo:[0,0,1] neg_hi:[0,0,1]
	v_pk_fma_f32 v[46:47], v[18:19], v[78:79], v[114:115] op_sel_hi:[1,0,1] neg_lo:[0,0,1] neg_hi:[0,0,1]
	v_pk_fma_f32 v[12:13], v[12:13], v[78:79], v[82:83] op_sel_hi:[1,0,1] neg_lo:[0,0,1] neg_hi:[0,0,1]
	v_pk_fma_f32 v[82:83], v[50:51], v[78:79], v[72:73] op_sel_hi:[1,0,1] neg_lo:[0,0,1] neg_hi:[0,0,1]
	v_pk_fma_f32 v[72:73], v[32:33], v[78:79], v[150:151] op_sel_hi:[1,0,1] neg_lo:[0,0,1] neg_hi:[0,0,1]
	v_pk_fma_f32 v[74:75], v[54:55], v[78:79], v[74:75] op_sel_hi:[1,0,1] neg_lo:[0,0,1] neg_hi:[0,0,1]
	v_pk_fma_f32 v[76:77], v[52:53], v[78:79], v[76:77] op_sel_hi:[1,0,1] neg_lo:[0,0,1] neg_hi:[0,0,1]
	v_pk_fma_f32 v[58:59], v[58:59], v[78:79], v[144:145] op_sel_hi:[1,0,1] neg_lo:[0,0,1] neg_hi:[0,0,1]
	v_pk_fma_f32 v[70:71], v[56:57], v[78:79], v[126:127] op_sel_hi:[1,0,1] neg_lo:[0,0,1] neg_hi:[0,0,1]
	v_pk_fma_f32 v[56:57], v[62:63], v[78:79], v[148:149] op_sel_hi:[1,0,1] neg_lo:[0,0,1] neg_hi:[0,0,1]
	v_pk_fma_f32 v[62:63], v[60:61], v[78:79], v[146:147] op_sel_hi:[1,0,1] neg_lo:[0,0,1] neg_hi:[0,0,1]
	v_pk_fma_f32 v[60:61], v[34:35], v[78:79], v[152:153] op_sel_hi:[1,0,1] neg_lo:[0,0,1] neg_hi:[0,0,1]
	v_pk_fma_f32 v[52:53], v[38:39], v[78:79], v[154:155] op_sel_hi:[1,0,1] neg_lo:[0,0,1] neg_hi:[0,0,1]
	v_pk_fma_f32 v[54:55], v[36:37], v[78:79], v[124:125] op_sel_hi:[1,0,1] neg_lo:[0,0,1] neg_hi:[0,0,1]
	v_pk_fma_f32 v[42:43], v[42:43], v[78:79], v[122:123] op_sel_hi:[1,0,1] neg_lo:[0,0,1] neg_hi:[0,0,1]
	v_pk_fma_f32 v[44:45], v[44:45], v[78:79], v[116:117] op_sel_hi:[1,0,1] neg_lo:[0,0,1] neg_hi:[0,0,1]
	v_pk_mul_f32 v[122:123], v[84:85], v[84:85]
	global_load_dwordx4 v[64:67], v[188:189], off
	v_pk_mul_f32 v[120:121], v[82:83], v[82:83]
	v_pk_mul_f32 v[126:127], v[76:77], v[76:77]
	v_pk_mul_f32 v[124:125], v[74:75], v[74:75]
	v_pk_mul_f32 v[146:147], v[70:71], v[70:71]
	v_pk_mul_f32 v[144:145], v[58:59], v[58:59]
	v_pk_mul_f32 v[150:151], v[62:63], v[62:63]
	v_pk_mul_f32 v[148:149], v[56:57], v[56:57]
	v_pk_mul_f32 v[154:155], v[72:73], v[72:73]
	v_pk_mul_f32 v[152:153], v[60:61], v[60:61]
	v_pk_mul_f32 v[158:159], v[54:55], v[54:55]
	v_pk_mul_f32 v[156:157], v[52:53], v[52:53]
	v_pk_mul_f32 v[162:163], v[48:49], v[48:49]
	v_pk_mul_f32 v[160:161], v[42:43], v[42:43]
	v_pk_mul_f32 v[166:167], v[44:45], v[44:45]
	v_pk_mul_f32 v[164:165], v[40:41], v[40:41]
	v_pk_mul_f32 v[172:173], v[46:47], v[46:47]
	v_pk_mul_f32 v[116:117], v[12:13], v[12:13]
	v_pk_mul_f32 v[118:119], v[14:15], v[14:15]
	global_load_dwordx2 v[114:115], v[68:69], off offset:16
	s_mov_b32 s8, 0x800000
	s_waitcnt vmcnt(2)
	v_lshlrev_b32_e32 v168, 16, v98
	v_and_b32_e32 v169, 0xffff0000, v98
	v_lshlrev_b32_e32 v98, 16, v99
	v_mul_f32_e32 v18, 0xbfb8aa3b, v168
	v_mul_f32_e32 v19, 0xbfb8aa3b, v169
	v_mul_f32_e32 v32, 0xbfb8aa3b, v98
	v_exp_f32_e32 v18, v18
	v_exp_f32_e32 v19, v19
	v_exp_f32_e32 v79, v32
	v_and_b32_e32 v99, 0xffff0000, v99
	v_mul_f32_e32 v33, 0xbfb8aa3b, v99
	v_add_f32_e32 v18, 1.0, v18
	v_add_f32_e32 v19, 1.0, v19
	v_exp_f32_e32 v174, v33
	v_rcp_f32_e32 v170, v18
	v_rcp_f32_e32 v171, v19
	v_pk_fma_f32 v[50:51], v[16:17], v[78:79], v[110:111] op_sel_hi:[1,0,1] neg_lo:[0,0,1] neg_hi:[0,0,1]
	v_pk_fma_f32 v[36:37], v[22:23], v[78:79], v[112:113] op_sel_hi:[1,0,1] neg_lo:[0,0,1] neg_hi:[0,0,1]
	v_pk_fma_f32 v[38:39], v[20:21], v[78:79], v[104:105] op_sel_hi:[1,0,1] neg_lo:[0,0,1] neg_hi:[0,0,1]
	v_pk_fma_f32 v[32:33], v[26:27], v[78:79], v[108:109] op_sel_hi:[1,0,1] neg_lo:[0,0,1] neg_hi:[0,0,1]
	v_pk_fma_f32 v[34:35], v[24:25], v[78:79], v[96:97] op_sel_hi:[1,0,1] neg_lo:[0,0,1] neg_hi:[0,0,1]
	v_pk_fma_f32 v[24:25], v[30:31], v[78:79], v[102:103] op_sel_hi:[1,0,1] neg_lo:[0,0,1] neg_hi:[0,0,1]
	v_pk_fma_f32 v[26:27], v[28:29], v[78:79], v[92:93] op_sel_hi:[1,0,1] neg_lo:[0,0,1] neg_hi:[0,0,1]
	s_waitcnt lgkmcnt(2)
	v_pk_fma_f32 v[20:21], v[2:3], v[78:79], v[106:107] op_sel_hi:[1,0,1] neg_lo:[0,0,1] neg_hi:[0,0,1]
	v_pk_fma_f32 v[22:23], v[0:1], v[78:79], v[94:95] op_sel_hi:[1,0,1] neg_lo:[0,0,1] neg_hi:[0,0,1]
	s_waitcnt lgkmcnt(0)
	v_pk_fma_f32 v[16:17], v[6:7], v[78:79], v[100:101] op_sel_hi:[1,0,1] neg_lo:[0,0,1] neg_hi:[0,0,1]
	v_pk_fma_f32 v[18:19], v[4:5], v[78:79], v[90:91] op_sel_hi:[1,0,1] neg_lo:[0,0,1] neg_hi:[0,0,1]
	v_pk_fma_f32 v[4:5], v[10:11], v[78:79], v[88:89] op_sel_hi:[1,0,1] neg_lo:[0,0,1] neg_hi:[0,0,1]
	v_pk_fma_f32 v[6:7], v[8:9], v[78:79], v[86:87] op_sel_hi:[1,0,1] neg_lo:[0,0,1] neg_hi:[0,0,1]
	v_add_f32_e32 v78, v122, v123
	v_add_f32_e32 v78, v78, v120
	v_add_f32_e32 v78, v78, v121
	v_add_f32_e32 v78, v78, v126
	v_add_f32_e32 v78, v78, v127
	v_add_f32_e32 v78, v78, v124
	v_add_f32_e32 v78, v78, v125
	v_add_f32_e32 v78, v78, v146
	v_add_f32_e32 v78, v78, v147
	v_add_f32_e32 v78, v78, v144
	v_add_f32_e32 v78, v78, v145
	v_add_f32_e32 v78, v78, v150
	v_add_f32_e32 v78, v78, v151
	v_add_f32_e32 v78, v78, v148
	v_add_f32_e32 v78, v78, v149
	v_add_f32_e32 v78, v78, v154
	v_add_f32_e32 v78, v78, v155
	v_add_f32_e32 v78, v78, v152
	v_add_f32_e32 v78, v78, v153
	v_add_f32_e32 v78, v78, v158
	v_add_f32_e32 v78, v78, v159
	v_add_f32_e32 v78, v78, v156
	v_add_f32_e32 v78, v78, v157
	v_add_f32_e32 v78, v78, v162
	v_add_f32_e32 v78, v78, v163
	v_add_f32_e32 v78, v78, v160
	v_add_f32_e32 v78, v78, v161
	v_add_f32_e32 v78, v78, v166
	v_add_f32_e32 v78, v78, v167
	v_add_f32_e32 v78, v78, v164
	v_pk_mul_f32 v[110:111], v[50:51], v[50:51]
	v_add_f32_e32 v78, v78, v165
	v_add_f32_e32 v78, v78, v110
	v_add_f32_e32 v78, v78, v111
	v_add_f32_e32 v78, v78, v172
	v_pk_mul_f32 v[104:105], v[38:39], v[38:39]
	v_add_f32_e32 v78, v78, v173
	v_add_f32_e32 v78, v78, v104
	v_pk_mul_f32 v[112:113], v[36:37], v[36:37]
	v_add_f32_e32 v78, v78, v105
	v_add_f32_e32 v78, v78, v112
	v_pk_mul_f32 v[96:97], v[34:35], v[34:35]
	v_add_f32_e32 v78, v78, v113
	v_add_f32_e32 v78, v78, v96
	v_pk_mul_f32 v[108:109], v[32:33], v[32:33]
	v_add_f32_e32 v78, v78, v97
	v_add_f32_e32 v78, v78, v108
	v_pk_mul_f32 v[28:29], v[26:27], v[26:27]
	v_add_f32_e32 v78, v78, v109
	v_add_f32_e32 v28, v78, v28
	v_pk_mul_f32 v[30:31], v[24:25], v[24:25]
	v_add_f32_e32 v28, v28, v29
	v_add_f32_e32 v28, v28, v30
	v_pk_mul_f32 v[0:1], v[22:23], v[22:23]
	v_add_f32_e32 v28, v28, v31
	v_add_f32_e32 v0, v28, v0
	v_pk_mul_f32 v[2:3], v[20:21], v[20:21]
	v_add_f32_e32 v0, v0, v1
	v_add_f32_e32 v0, v0, v2
	v_pk_mul_f32 v[90:91], v[18:19], v[18:19]
	v_add_f32_e32 v0, v0, v3
	v_add_f32_e32 v0, v0, v90
	v_pk_mul_f32 v[92:93], v[16:17], v[16:17]
	v_add_f32_e32 v0, v0, v91
	v_add_f32_e32 v0, v0, v92
	v_pk_mul_f32 v[8:9], v[6:7], v[6:7]
	v_add_f32_e32 v0, v0, v93
	v_add_f32_e32 v0, v0, v8
	v_pk_mul_f32 v[10:11], v[4:5], v[4:5]
	v_add_f32_e32 v0, v0, v9
	v_add_f32_e32 v0, v0, v10
	v_add_f32_e32 v0, v0, v11
	v_add_f32_e32 v0, v0, v116
	v_add_f32_e32 v0, v0, v117
	v_add_f32_e32 v0, v0, v118
	v_add_f32_e32 v2, v0, v119
	ds_bpermute_b32 v3, v244, v2
	v_add_f32_e32 v0, 1.0, v79
	v_add_f32_e32 v1, 1.0, v174
	v_rcp_f32_e32 v0, v0
	v_rcp_f32_e32 v1, v1
	s_waitcnt lgkmcnt(0)
	v_add_f32_e32 v2, v2, v3
	v_fmamk_f32 v2, v2, 0x3c000000, v233
	v_mul_f32_e32 v3, 0x4b800000, v2
	v_cmp_gt_f32_e32 vcc, s8, v2
	v_pk_mul_f32 v[0:1], v[0:1], v[98:99]
	v_lshl_add_u64 v[8:9], v[192:193], 0, v[80:81]
	v_cndmask_b32_e32 v2, v2, v3, vcc
	v_rsq_f32_e32 v10, v2
	v_pk_mul_f32 v[2:3], v[170:171], v[168:169]
	s_waitcnt vmcnt(0)
	v_lshlrev_b32_e32 v30, 16, v114
	v_and_b32_e32 v31, 0xffff0000, v114
	v_mul_f32_e32 v11, 0x45800000, v10
	v_cndmask_b32_e32 v10, v10, v11, vcc
	v_mul_f32_e32 v10, 0x3f24fd5c, v10
	v_pk_mul_f32 v[28:29], v[84:85], v[10:11] op_sel_hi:[1,0]
	s_nop 0
	v_pk_mul_f32 v[28:29], v[64:65], v[28:29]
	v_mul_f32_e32 v65, 0xbfb8aa3b, v31
	v_pk_mul_f32 v[2:3], v[2:3], v[28:29]
	v_pk_mul_f32 v[28:29], v[82:83], v[10:11] op_sel_hi:[1,0]
	v_cvt_pk_bf16_f32 v2, v2, v3
	v_pk_mul_f32 v[28:29], v[66:67], v[28:29]
	v_mul_f32_e32 v11, 0xbfb8aa3b, v30
	v_pk_mul_f32 v[0:1], v[0:1], v[28:29]
	v_exp_f32_e32 v11, v11
	v_cvt_pk_bf16_f32 v3, v0, v1
	global_store_dwordx2 v[8:9], v[2:3], off
	global_load_dwordx4 v[0:3], v[188:189], off offset:32
	s_nop 0
	global_load_dwordx2 v[28:29], v[68:69], off offset:32
	v_exp_f32_e32 v67, v65
	v_lshlrev_b32_e32 v64, 16, v115
	v_add_f32_e32 v11, 1.0, v11
	v_and_b32_e32 v65, 0xffff0000, v115
	v_rcp_f32_e32 v66, v11
	v_add_f32_e32 v11, 1.0, v67
	v_mul_f32_e32 v67, 0xbfb8aa3b, v64
	v_exp_f32_e32 v78, v67
	v_mul_f32_e32 v67, 0xbfb8aa3b, v65
	v_exp_f32_e32 v79, v67
	v_rcp_f32_e32 v67, v11
	v_add_f32_e32 v11, 1.0, v78
	v_rcp_f32_e32 v78, v11
	v_add_f32_e32 v11, 1.0, v79
	v_rcp_f32_e32 v79, v11
	v_pk_mul_f32 v[30:31], v[66:67], v[30:31]
	v_pk_mul_f32 v[66:67], v[76:77], v[10:11] op_sel_hi:[1,0]
	v_pk_mul_f32 v[64:65], v[78:79], v[64:65]
	s_waitcnt vmcnt(1)
	v_pk_mul_f32 v[0:1], v[0:1], v[66:67]
	s_nop 0
	v_pk_mul_f32 v[0:1], v[30:31], v[0:1]
	v_pk_mul_f32 v[30:31], v[74:75], v[10:11] op_sel_hi:[1,0]
	v_cvt_pk_bf16_f32 v0, v0, v1
	v_pk_mul_f32 v[2:3], v[2:3], v[30:31]
	s_nop 0
	v_pk_mul_f32 v[2:3], v[2:3], v[64:65]
	s_waitcnt vmcnt(0)
	v_lshlrev_b32_e32 v64, 16, v28
	v_cvt_pk_bf16_f32 v1, v2, v3
	global_store_dwordx2 v[8:9], v[0:1], off offset:16
	global_load_dwordx4 v[0:3], v[188:189], off offset:64
	s_nop 0
	global_load_dwordx2 v[30:31], v[68:69], off offset:48
	v_and_b32_e32 v65, 0xffff0000, v28
	v_mul_f32_e32 v11, 0xbfb8aa3b, v64
	v_exp_f32_e32 v11, v11
	v_mul_f32_e32 v66, 0xbfb8aa3b, v65
	v_exp_f32_e32 v67, v66
	v_lshlrev_b32_e32 v28, 16, v29
	v_add_f32_e32 v11, 1.0, v11
	v_and_b32_e32 v29, 0xffff0000, v29
	v_rcp_f32_e32 v66, v11
	v_add_f32_e32 v11, 1.0, v67
	v_mul_f32_e32 v67, 0xbfb8aa3b, v28
	v_exp_f32_e32 v74, v67
	v_mul_f32_e32 v67, 0xbfb8aa3b, v29
	v_exp_f32_e32 v75, v67
	v_rcp_f32_e32 v67, v11
	v_add_f32_e32 v11, 1.0, v74
	v_rcp_f32_e32 v74, v11
	v_add_f32_e32 v11, 1.0, v75
	v_rcp_f32_e32 v75, v11
	v_pk_mul_f32 v[64:65], v[66:67], v[64:65]
	v_pk_mul_f32 v[66:67], v[70:71], v[10:11] op_sel_hi:[1,0]
	v_pk_mul_f32 v[58:59], v[58:59], v[10:11] op_sel_hi:[1,0]
	v_pk_mul_f32 v[28:29], v[74:75], v[28:29]
	s_waitcnt vmcnt(1)
	v_pk_mul_f32 v[0:1], v[66:67], v[0:1]
	v_pk_mul_f32 v[2:3], v[58:59], v[2:3]
	v_pk_mul_f32 v[0:1], v[0:1], v[64:65]
	v_pk_mul_f32 v[2:3], v[2:3], v[28:29]
	v_cvt_pk_bf16_f32 v0, v0, v1
	v_cvt_pk_bf16_f32 v1, v2, v3
	global_store_dwordx2 v[8:9], v[0:1], off offset:32
	global_load_dwordx4 v[0:3], v[188:189], off offset:96
	s_nop 0
	global_load_dwordx2 v[28:29], v[68:69], off offset:64
	s_waitcnt vmcnt(3)
	v_lshlrev_b32_e32 v58, 16, v30
	v_and_b32_e32 v59, 0xffff0000, v30
	v_lshlrev_b32_e32 v30, 16, v31
	v_and_b32_e32 v31, 0xffff0000, v31
	v_mul_f32_e32 v11, 0xbfb8aa3b, v58
	v_mul_f32_e32 v64, 0xbfb8aa3b, v59
	v_mul_f32_e32 v65, 0xbfb8aa3b, v30
	v_mul_f32_e32 v66, 0xbfb8aa3b, v31
	v_exp_f32_e32 v11, v11
	v_exp_f32_e32 v64, v64
	v_exp_f32_e32 v65, v65
	v_exp_f32_e32 v66, v66
	v_add_f32_e32 v11, 1.0, v11
	v_add_f32_e32 v67, 1.0, v64
	v_add_f32_e32 v70, 1.0, v65
	v_add_f32_e32 v71, 1.0, v66
	v_rcp_f32_e32 v64, v11
	v_rcp_f32_e32 v65, v67
	v_rcp_f32_e32 v66, v70
	v_rcp_f32_e32 v67, v71
	v_pk_mul_f32 v[62:63], v[62:63], v[10:11] op_sel_hi:[1,0]
	v_pk_mul_f32 v[56:57], v[56:57], v[10:11] op_sel_hi:[1,0]
	v_pk_mul_f32 v[58:59], v[64:65], v[58:59]
	v_pk_mul_f32 v[30:31], v[66:67], v[30:31]
	s_waitcnt vmcnt(1)
	v_pk_mul_f32 v[0:1], v[62:63], v[0:1]
	v_pk_mul_f32 v[2:3], v[56:57], v[2:3]
	v_pk_mul_f32 v[0:1], v[0:1], v[58:59]
	v_pk_mul_f32 v[2:3], v[2:3], v[30:31]
	v_cvt_pk_bf16_f32 v0, v0, v1
	v_cvt_pk_bf16_f32 v1, v2, v3
	global_store_dwordx2 v[8:9], v[0:1], off offset:48
	global_load_dwordx4 v[0:3], v[188:189], off offset:128
	s_nop 0
	global_load_dwordx2 v[30:31], v[68:69], off offset:80
	s_waitcnt vmcnt(3)
	v_lshlrev_b32_e32 v56, 16, v28
	v_and_b32_e32 v57, 0xffff0000, v28
	v_lshlrev_b32_e32 v28, 16, v29
	v_and_b32_e32 v29, 0xffff0000, v29
	v_mul_f32_e32 v11, 0xbfb8aa3b, v56
	v_mul_f32_e32 v58, 0xbfb8aa3b, v57
	v_mul_f32_e32 v59, 0xbfb8aa3b, v28
	v_mul_f32_e32 v62, 0xbfb8aa3b, v29
	v_exp_f32_e32 v11, v11
	v_exp_f32_e32 v58, v58
	v_exp_f32_e32 v59, v59
	v_exp_f32_e32 v62, v62
	v_add_f32_e32 v11, 1.0, v11
	v_add_f32_e32 v63, 1.0, v58
	v_add_f32_e32 v64, 1.0, v59
	v_add_f32_e32 v65, 1.0, v62
	v_rcp_f32_e32 v58, v11
	v_rcp_f32_e32 v59, v63
	v_rcp_f32_e32 v62, v64
	v_rcp_f32_e32 v63, v65
	v_pk_mul_f32 v[64:65], v[72:73], v[10:11] op_sel_hi:[1,0]
	v_pk_mul_f32 v[60:61], v[60:61], v[10:11] op_sel_hi:[1,0]
	v_pk_mul_f32 v[56:57], v[58:59], v[56:57]
	v_pk_mul_f32 v[28:29], v[62:63], v[28:29]
	s_waitcnt vmcnt(1)
	v_pk_mul_f32 v[0:1], v[64:65], v[0:1]
	v_pk_mul_f32 v[2:3], v[60:61], v[2:3]
	v_pk_mul_f32 v[0:1], v[0:1], v[56:57]
	v_pk_mul_f32 v[2:3], v[2:3], v[28:29]
	v_cvt_pk_bf16_f32 v0, v0, v1
	v_cvt_pk_bf16_f32 v1, v2, v3
	global_store_dwordx2 v[8:9], v[0:1], off offset:64
	global_load_dwordx4 v[0:3], v[188:189], off offset:160
	s_nop 0
	global_load_dwordx2 v[28:29], v[68:69], off offset:96
	s_waitcnt vmcnt(3)
	v_lshlrev_b32_e32 v56, 16, v30
	v_and_b32_e32 v57, 0xffff0000, v30
	v_lshlrev_b32_e32 v30, 16, v31
	v_and_b32_e32 v31, 0xffff0000, v31
	v_mul_f32_e32 v11, 0xbfb8aa3b, v56
	v_mul_f32_e32 v58, 0xbfb8aa3b, v57
	v_mul_f32_e32 v59, 0xbfb8aa3b, v30
	v_mul_f32_e32 v60, 0xbfb8aa3b, v31
	v_exp_f32_e32 v11, v11
	v_exp_f32_e32 v58, v58
	v_exp_f32_e32 v59, v59
	v_exp_f32_e32 v60, v60
	v_add_f32_e32 v11, 1.0, v11
	v_add_f32_e32 v61, 1.0, v58
	v_add_f32_e32 v62, 1.0, v59
	v_add_f32_e32 v63, 1.0, v60
	v_rcp_f32_e32 v58, v11
	v_rcp_f32_e32 v59, v61
	v_rcp_f32_e32 v60, v62
	v_rcp_f32_e32 v61, v63
	v_pk_mul_f32 v[54:55], v[54:55], v[10:11] op_sel_hi:[1,0]
	v_pk_mul_f32 v[52:53], v[52:53], v[10:11] op_sel_hi:[1,0]
	v_pk_mul_f32 v[56:57], v[58:59], v[56:57]
	v_pk_mul_f32 v[30:31], v[60:61], v[30:31]
	s_waitcnt vmcnt(1)
	v_pk_mul_f32 v[0:1], v[54:55], v[0:1]
	v_pk_mul_f32 v[2:3], v[52:53], v[2:3]
	v_pk_mul_f32 v[0:1], v[0:1], v[56:57]
	v_pk_mul_f32 v[2:3], v[2:3], v[30:31]
	v_cvt_pk_bf16_f32 v0, v0, v1
	v_cvt_pk_bf16_f32 v1, v2, v3
	global_store_dwordx2 v[8:9], v[0:1], off offset:80
	global_load_dwordx4 v[0:3], v[188:189], off offset:192
	s_nop 0
	global_load_dwordx2 v[30:31], v[68:69], off offset:112
	s_waitcnt vmcnt(3)
	v_lshlrev_b32_e32 v52, 16, v28
	v_and_b32_e32 v53, 0xffff0000, v28
	v_lshlrev_b32_e32 v28, 16, v29
	v_and_b32_e32 v29, 0xffff0000, v29
	v_mul_f32_e32 v11, 0xbfb8aa3b, v52
	v_mul_f32_e32 v54, 0xbfb8aa3b, v53
	v_mul_f32_e32 v55, 0xbfb8aa3b, v28
	v_mul_f32_e32 v56, 0xbfb8aa3b, v29
	v_exp_f32_e32 v11, v11
	v_exp_f32_e32 v54, v54
	v_exp_f32_e32 v55, v55
	v_exp_f32_e32 v56, v56
	v_add_f32_e32 v11, 1.0, v11
	v_add_f32_e32 v57, 1.0, v54
	v_add_f32_e32 v58, 1.0, v55
	v_add_f32_e32 v59, 1.0, v56
	v_rcp_f32_e32 v54, v11
	v_rcp_f32_e32 v55, v57
	v_rcp_f32_e32 v56, v58
	v_rcp_f32_e32 v57, v59
	v_pk_mul_f32 v[48:49], v[48:49], v[10:11] op_sel_hi:[1,0]
	v_pk_mul_f32 v[42:43], v[42:43], v[10:11] op_sel_hi:[1,0]
	v_pk_mul_f32 v[52:53], v[54:55], v[52:53]
	v_pk_mul_f32 v[28:29], v[56:57], v[28:29]
	s_waitcnt vmcnt(1)
	v_pk_mul_f32 v[0:1], v[48:49], v[0:1]
	v_pk_mul_f32 v[2:3], v[42:43], v[2:3]
	v_pk_mul_f32 v[0:1], v[0:1], v[52:53]
	v_pk_mul_f32 v[2:3], v[2:3], v[28:29]
	v_cvt_pk_bf16_f32 v0, v0, v1
	v_cvt_pk_bf16_f32 v1, v2, v3
	global_store_dwordx2 v[8:9], v[0:1], off offset:96
	global_load_dwordx4 v[0:3], v[188:189], off offset:224
	s_nop 0
	global_load_dwordx2 v[28:29], v[68:69], off offset:128
	s_waitcnt vmcnt(3)
	v_lshlrev_b32_e32 v42, 16, v30
	v_and_b32_e32 v43, 0xffff0000, v30
	v_lshlrev_b32_e32 v30, 16, v31
	v_and_b32_e32 v31, 0xffff0000, v31
	v_mul_f32_e32 v11, 0xbfb8aa3b, v42
	v_mul_f32_e32 v48, 0xbfb8aa3b, v43
	v_mul_f32_e32 v49, 0xbfb8aa3b, v30
	v_mul_f32_e32 v52, 0xbfb8aa3b, v31
	v_exp_f32_e32 v11, v11
	v_exp_f32_e32 v48, v48
	v_exp_f32_e32 v49, v49
	v_exp_f32_e32 v52, v52
	v_add_f32_e32 v11, 1.0, v11
	v_add_f32_e32 v53, 1.0, v48
	v_add_f32_e32 v54, 1.0, v49
	v_add_f32_e32 v55, 1.0, v52
	v_rcp_f32_e32 v48, v11
	v_rcp_f32_e32 v49, v53
	v_rcp_f32_e32 v52, v54
	v_rcp_f32_e32 v53, v55
	v_pk_mul_f32 v[44:45], v[44:45], v[10:11] op_sel_hi:[1,0]
	v_pk_mul_f32 v[40:41], v[40:41], v[10:11] op_sel_hi:[1,0]
	v_pk_mul_f32 v[42:43], v[48:49], v[42:43]
	v_pk_mul_f32 v[30:31], v[52:53], v[30:31]
	s_waitcnt vmcnt(1)
	v_pk_mul_f32 v[0:1], v[44:45], v[0:1]
	v_pk_mul_f32 v[2:3], v[40:41], v[2:3]
	v_pk_mul_f32 v[0:1], v[0:1], v[42:43]
	v_pk_mul_f32 v[2:3], v[2:3], v[30:31]
	v_cvt_pk_bf16_f32 v0, v0, v1
	v_cvt_pk_bf16_f32 v1, v2, v3
	global_store_dwordx2 v[8:9], v[0:1], off offset:112
	global_load_dwordx4 v[0:3], v[188:189], off offset:256
	s_nop 0
	global_load_dwordx2 v[30:31], v[68:69], off offset:144
	s_waitcnt vmcnt(3)
	v_lshlrev_b32_e32 v40, 16, v28
	v_and_b32_e32 v41, 0xffff0000, v28
	v_lshlrev_b32_e32 v28, 16, v29
	v_and_b32_e32 v29, 0xffff0000, v29
	v_mul_f32_e32 v11, 0xbfb8aa3b, v40
	v_mul_f32_e32 v42, 0xbfb8aa3b, v41
	v_mul_f32_e32 v43, 0xbfb8aa3b, v28
	v_mul_f32_e32 v44, 0xbfb8aa3b, v29
	v_exp_f32_e32 v11, v11
	v_exp_f32_e32 v42, v42
	v_exp_f32_e32 v43, v43
	v_exp_f32_e32 v44, v44
	v_add_f32_e32 v11, 1.0, v11
	v_add_f32_e32 v45, 1.0, v42
	v_add_f32_e32 v48, 1.0, v43
	v_add_f32_e32 v49, 1.0, v44
	v_rcp_f32_e32 v42, v11
	v_rcp_f32_e32 v43, v45
	v_rcp_f32_e32 v44, v48
	v_rcp_f32_e32 v45, v49
	v_pk_mul_f32 v[48:49], v[50:51], v[10:11] op_sel_hi:[1,0]
	v_pk_mul_f32 v[46:47], v[46:47], v[10:11] op_sel_hi:[1,0]
	v_pk_mul_f32 v[40:41], v[42:43], v[40:41]
	v_pk_mul_f32 v[28:29], v[44:45], v[28:29]
	s_waitcnt vmcnt(1)
	v_pk_mul_f32 v[0:1], v[48:49], v[0:1]
	v_pk_mul_f32 v[2:3], v[46:47], v[2:3]
	v_pk_mul_f32 v[0:1], v[0:1], v[40:41]
	v_pk_mul_f32 v[2:3], v[2:3], v[28:29]
	v_cvt_pk_bf16_f32 v0, v0, v1
	v_cvt_pk_bf16_f32 v1, v2, v3
	global_store_dwordx2 v[8:9], v[0:1], off offset:128
	global_load_dwordx4 v[0:3], v[188:189], off offset:288
	s_nop 0
	global_load_dwordx2 v[28:29], v[68:69], off offset:160
	s_waitcnt vmcnt(3)
	v_lshlrev_b32_e32 v40, 16, v30
	v_and_b32_e32 v41, 0xffff0000, v30
	v_lshlrev_b32_e32 v30, 16, v31
	v_and_b32_e32 v31, 0xffff0000, v31
	v_mul_f32_e32 v11, 0xbfb8aa3b, v40
	v_mul_f32_e32 v42, 0xbfb8aa3b, v41
	v_mul_f32_e32 v43, 0xbfb8aa3b, v30
	v_mul_f32_e32 v44, 0xbfb8aa3b, v31
	v_exp_f32_e32 v11, v11
	v_exp_f32_e32 v42, v42
	v_exp_f32_e32 v43, v43
	v_exp_f32_e32 v44, v44
	v_add_f32_e32 v11, 1.0, v11
	v_add_f32_e32 v45, 1.0, v42
	v_add_f32_e32 v46, 1.0, v43
	v_add_f32_e32 v47, 1.0, v44
	v_rcp_f32_e32 v42, v11
	v_rcp_f32_e32 v43, v45
	v_rcp_f32_e32 v44, v46
	v_rcp_f32_e32 v45, v47
	v_pk_mul_f32 v[38:39], v[38:39], v[10:11] op_sel_hi:[1,0]
	v_pk_mul_f32 v[36:37], v[36:37], v[10:11] op_sel_hi:[1,0]
	v_pk_mul_f32 v[40:41], v[42:43], v[40:41]
	v_pk_mul_f32 v[30:31], v[44:45], v[30:31]
	s_waitcnt vmcnt(1)
	v_pk_mul_f32 v[0:1], v[38:39], v[0:1]
	v_pk_mul_f32 v[2:3], v[36:37], v[2:3]
	v_pk_mul_f32 v[0:1], v[0:1], v[40:41]
	v_pk_mul_f32 v[2:3], v[2:3], v[30:31]
	v_cvt_pk_bf16_f32 v0, v0, v1
	v_cvt_pk_bf16_f32 v1, v2, v3
	global_store_dwordx2 v[8:9], v[0:1], off offset:144
	global_load_dwordx4 v[0:3], v[188:189], off offset:320
	s_nop 0
	global_load_dwordx2 v[30:31], v[68:69], off offset:176
	s_waitcnt vmcnt(3)
	v_lshlrev_b32_e32 v36, 16, v28
	v_and_b32_e32 v37, 0xffff0000, v28
	v_lshlrev_b32_e32 v28, 16, v29
	v_and_b32_e32 v29, 0xffff0000, v29
	v_mul_f32_e32 v11, 0xbfb8aa3b, v36
	v_mul_f32_e32 v38, 0xbfb8aa3b, v37
	v_mul_f32_e32 v39, 0xbfb8aa3b, v28
	v_mul_f32_e32 v40, 0xbfb8aa3b, v29
	v_exp_f32_e32 v11, v11
	v_exp_f32_e32 v38, v38
	v_exp_f32_e32 v39, v39
	v_exp_f32_e32 v40, v40
	v_add_f32_e32 v11, 1.0, v11
	v_add_f32_e32 v41, 1.0, v38
	v_add_f32_e32 v42, 1.0, v39
	v_add_f32_e32 v43, 1.0, v40
	v_rcp_f32_e32 v38, v11
	v_rcp_f32_e32 v39, v41
	v_rcp_f32_e32 v40, v42
	v_rcp_f32_e32 v41, v43
	v_pk_mul_f32 v[34:35], v[34:35], v[10:11] op_sel_hi:[1,0]
	v_pk_mul_f32 v[32:33], v[32:33], v[10:11] op_sel_hi:[1,0]
	v_pk_mul_f32 v[36:37], v[38:39], v[36:37]
	v_pk_mul_f32 v[28:29], v[40:41], v[28:29]
	s_waitcnt vmcnt(1)
	v_pk_mul_f32 v[0:1], v[34:35], v[0:1]
	v_pk_mul_f32 v[2:3], v[32:33], v[2:3]
	v_pk_mul_f32 v[0:1], v[0:1], v[36:37]
	v_pk_mul_f32 v[2:3], v[2:3], v[28:29]
	v_cvt_pk_bf16_f32 v0, v0, v1
	v_cvt_pk_bf16_f32 v1, v2, v3
	global_store_dwordx2 v[8:9], v[0:1], off offset:160
	global_load_dwordx4 v[0:3], v[188:189], off offset:352
	s_nop 0
	global_load_dwordx2 v[28:29], v[68:69], off offset:192
	s_waitcnt vmcnt(3)
	v_lshlrev_b32_e32 v32, 16, v30
	v_and_b32_e32 v33, 0xffff0000, v30
	v_lshlrev_b32_e32 v30, 16, v31
	v_and_b32_e32 v31, 0xffff0000, v31
	v_mul_f32_e32 v11, 0xbfb8aa3b, v32
	v_mul_f32_e32 v34, 0xbfb8aa3b, v33
	v_mul_f32_e32 v35, 0xbfb8aa3b, v30
	v_mul_f32_e32 v36, 0xbfb8aa3b, v31
	v_exp_f32_e32 v11, v11
	v_exp_f32_e32 v34, v34
	v_exp_f32_e32 v35, v35
	v_exp_f32_e32 v36, v36
	v_add_f32_e32 v11, 1.0, v11
	v_add_f32_e32 v37, 1.0, v34
	v_add_f32_e32 v38, 1.0, v35
	v_add_f32_e32 v39, 1.0, v36
	v_rcp_f32_e32 v34, v11
	v_rcp_f32_e32 v35, v37
	v_rcp_f32_e32 v36, v38
	v_rcp_f32_e32 v37, v39
	v_pk_mul_f32 v[26:27], v[26:27], v[10:11] op_sel_hi:[1,0]
	v_pk_mul_f32 v[24:25], v[24:25], v[10:11] op_sel_hi:[1,0]
	v_pk_mul_f32 v[32:33], v[34:35], v[32:33]
	v_pk_mul_f32 v[30:31], v[36:37], v[30:31]
	s_waitcnt vmcnt(1)
	v_pk_mul_f32 v[0:1], v[26:27], v[0:1]
	v_pk_mul_f32 v[2:3], v[24:25], v[2:3]
	v_pk_mul_f32 v[0:1], v[0:1], v[32:33]
	v_pk_mul_f32 v[2:3], v[2:3], v[30:31]
	v_cvt_pk_bf16_f32 v0, v0, v1
	v_cvt_pk_bf16_f32 v1, v2, v3
	global_store_dwordx2 v[8:9], v[0:1], off offset:176
	global_load_dwordx4 v[0:3], v[188:189], off offset:384
	s_nop 0
	global_load_dwordx2 v[24:25], v[68:69], off offset:208
	s_waitcnt vmcnt(3)
	v_lshlrev_b32_e32 v26, 16, v28
	v_and_b32_e32 v27, 0xffff0000, v28
	v_lshlrev_b32_e32 v28, 16, v29
	v_and_b32_e32 v29, 0xffff0000, v29
	v_mul_f32_e32 v11, 0xbfb8aa3b, v26
	v_mul_f32_e32 v30, 0xbfb8aa3b, v27
	v_mul_f32_e32 v31, 0xbfb8aa3b, v28
	v_mul_f32_e32 v32, 0xbfb8aa3b, v29
	v_exp_f32_e32 v11, v11
	v_exp_f32_e32 v30, v30
	v_exp_f32_e32 v31, v31
	v_exp_f32_e32 v32, v32
	v_add_f32_e32 v11, 1.0, v11
	v_add_f32_e32 v33, 1.0, v30
	v_add_f32_e32 v34, 1.0, v31
	v_add_f32_e32 v35, 1.0, v32
	v_rcp_f32_e32 v30, v11
	v_rcp_f32_e32 v31, v33
	v_rcp_f32_e32 v32, v34
	v_rcp_f32_e32 v33, v35
	v_pk_mul_f32 v[22:23], v[22:23], v[10:11] op_sel_hi:[1,0]
	v_pk_mul_f32 v[20:21], v[20:21], v[10:11] op_sel_hi:[1,0]
	v_pk_mul_f32 v[26:27], v[30:31], v[26:27]
	v_pk_mul_f32 v[28:29], v[32:33], v[28:29]
	s_waitcnt vmcnt(1)
	v_pk_mul_f32 v[0:1], v[22:23], v[0:1]
	v_pk_mul_f32 v[2:3], v[20:21], v[2:3]
	v_pk_mul_f32 v[0:1], v[0:1], v[26:27]
	v_pk_mul_f32 v[2:3], v[2:3], v[28:29]
	v_cvt_pk_bf16_f32 v0, v0, v1
	v_cvt_pk_bf16_f32 v1, v2, v3
	global_store_dwordx2 v[8:9], v[0:1], off offset:192
	global_load_dwordx4 v[0:3], v[188:189], off offset:416
	s_nop 0
	global_load_dwordx2 v[20:21], v[68:69], off offset:224
	s_waitcnt vmcnt(3)
	v_lshlrev_b32_e32 v22, 16, v24
	v_and_b32_e32 v23, 0xffff0000, v24
	v_lshlrev_b32_e32 v24, 16, v25
	v_and_b32_e32 v25, 0xffff0000, v25
	v_mul_f32_e32 v11, 0xbfb8aa3b, v22
	v_mul_f32_e32 v26, 0xbfb8aa3b, v23
	v_mul_f32_e32 v27, 0xbfb8aa3b, v24
	v_mul_f32_e32 v28, 0xbfb8aa3b, v25
	v_exp_f32_e32 v11, v11
	v_exp_f32_e32 v26, v26
	v_exp_f32_e32 v27, v27
	v_exp_f32_e32 v28, v28
	v_add_f32_e32 v11, 1.0, v11
	v_add_f32_e32 v29, 1.0, v26
	v_add_f32_e32 v30, 1.0, v27
	v_add_f32_e32 v31, 1.0, v28
	v_rcp_f32_e32 v26, v11
	v_rcp_f32_e32 v27, v29
	v_rcp_f32_e32 v28, v30
	v_rcp_f32_e32 v29, v31
	v_pk_mul_f32 v[18:19], v[18:19], v[10:11] op_sel_hi:[1,0]
	v_pk_mul_f32 v[16:17], v[16:17], v[10:11] op_sel_hi:[1,0]
	v_pk_mul_f32 v[22:23], v[26:27], v[22:23]
	v_pk_mul_f32 v[24:25], v[28:29], v[24:25]
	s_waitcnt vmcnt(1)
	v_pk_mul_f32 v[0:1], v[18:19], v[0:1]
	v_pk_mul_f32 v[2:3], v[16:17], v[2:3]
	v_pk_mul_f32 v[0:1], v[0:1], v[22:23]
	v_pk_mul_f32 v[2:3], v[2:3], v[24:25]
	v_cvt_pk_bf16_f32 v0, v0, v1
	v_cvt_pk_bf16_f32 v1, v2, v3
	global_store_dwordx2 v[8:9], v[0:1], off offset:208
	global_load_dwordx4 v[0:3], v[188:189], off offset:448
	s_nop 0
	global_load_dwordx2 v[16:17], v[68:69], off offset:240
	s_waitcnt vmcnt(3)
	v_lshlrev_b32_e32 v18, 16, v20
	v_and_b32_e32 v19, 0xffff0000, v20
	v_lshlrev_b32_e32 v20, 16, v21
	v_and_b32_e32 v21, 0xffff0000, v21
	v_mul_f32_e32 v11, 0xbfb8aa3b, v18
	v_mul_f32_e32 v22, 0xbfb8aa3b, v19
	v_mul_f32_e32 v23, 0xbfb8aa3b, v20
	v_mul_f32_e32 v24, 0xbfb8aa3b, v21
	v_exp_f32_e32 v11, v11
	v_exp_f32_e32 v22, v22
	v_exp_f32_e32 v23, v23
	v_exp_f32_e32 v24, v24
	v_add_f32_e32 v11, 1.0, v11
	v_add_f32_e32 v25, 1.0, v22
	v_add_f32_e32 v26, 1.0, v23
	v_add_f32_e32 v27, 1.0, v24
	v_rcp_f32_e32 v22, v11
	v_rcp_f32_e32 v23, v25
	v_rcp_f32_e32 v24, v26
	v_rcp_f32_e32 v25, v27
	v_pk_mul_f32 v[6:7], v[6:7], v[10:11] op_sel_hi:[1,0]
	v_pk_mul_f32 v[4:5], v[4:5], v[10:11] op_sel_hi:[1,0]
	v_pk_mul_f32 v[18:19], v[22:23], v[18:19]
	v_pk_mul_f32 v[20:21], v[24:25], v[20:21]
	s_waitcnt vmcnt(1)
	v_pk_mul_f32 v[0:1], v[6:7], v[0:1]
	v_pk_mul_f32 v[2:3], v[4:5], v[2:3]
	v_pk_mul_f32 v[0:1], v[0:1], v[18:19]
	v_pk_mul_f32 v[2:3], v[2:3], v[20:21]
	v_cvt_pk_bf16_f32 v0, v0, v1
	v_cvt_pk_bf16_f32 v1, v2, v3
	global_store_dwordx2 v[8:9], v[0:1], off offset:224
	global_load_dwordx4 v[0:3], v[188:189], off offset:480
	s_waitcnt vmcnt(2)
	v_lshlrev_b32_e32 v4, 16, v16
	v_and_b32_e32 v5, 0xffff0000, v16
	v_lshlrev_b32_e32 v6, 16, v17
	v_and_b32_e32 v7, 0xffff0000, v17
	v_mul_f32_e32 v11, 0xbfb8aa3b, v4
	v_mul_f32_e32 v16, 0xbfb8aa3b, v5
	v_mul_f32_e32 v17, 0xbfb8aa3b, v6
	v_mul_f32_e32 v18, 0xbfb8aa3b, v7
	v_exp_f32_e32 v11, v11
	v_exp_f32_e32 v16, v16
	v_exp_f32_e32 v17, v17
	v_exp_f32_e32 v18, v18
	v_add_f32_e32 v11, 1.0, v11
	v_add_f32_e32 v19, 1.0, v16
	v_add_f32_e32 v20, 1.0, v17
	v_add_f32_e32 v21, 1.0, v18
	v_rcp_f32_e32 v16, v11
	v_rcp_f32_e32 v17, v19
	v_rcp_f32_e32 v18, v20
	v_rcp_f32_e32 v19, v21
	v_pk_mul_f32 v[12:13], v[12:13], v[10:11] op_sel_hi:[1,0]
	v_pk_mul_f32 v[10:11], v[14:15], v[10:11] op_sel_hi:[1,0]
	v_pk_mul_f32 v[4:5], v[16:17], v[4:5]
	v_pk_mul_f32 v[6:7], v[18:19], v[6:7]
	s_waitcnt vmcnt(0)
	v_pk_mul_f32 v[0:1], v[12:13], v[0:1]
	v_pk_mul_f32 v[2:3], v[10:11], v[2:3]
	v_pk_mul_f32 v[0:1], v[0:1], v[4:5]
	v_pk_mul_f32 v[2:3], v[2:3], v[6:7]
	v_cvt_pk_bf16_f32 v0, v0, v1
	v_cvt_pk_bf16_f32 v1, v2, v3
	global_store_dwordx2 v[8:9], v[0:1], off offset:240
	s_branch .LBB0_1120
